# next layer's W_in conversion moved from the LN phases into the idle second round of the out-proj GEMM phases (384 WGs not sharing a CU with a second tile)
# baseline (speedup 1.0000x reference)
.LBB0_58:
	s_andn2_b64 vcc, exec, s[40:41]
	s_cbranch_vccnz .LBB0_145
	v_readlane_b32 s0, v254, 55
	v_lshl_add_u32 v0, s20, 8, v134
	s_cmp_lg_u32 s0, 3
	v_ashrrev_i32_e32 v130, 6, v0
	s_cselect_b64 s[40:41], -1, 0
	s_cmp_eq_u32 s0, 3
	s_mov_b32 s35, s16
	s_mov_b32 s101, 0
	s_mov_b32 s25, s13
	v_lshlrev_b32_e32 v133, 2, v134
	s_cselect_b64 s[42:43], -1, 0
	v_cmp_gt_i32_e32 vcc, s14, v130
	s_and_saveexec_b64 s[16:17], vcc
	s_cbranch_execz .LBB0_104
	s_lshl_b32 s4, s34, 2
	s_add_u32 s18, s94, 0xfe40000
	v_readlane_b32 s10, v254, 55
	s_addc_u32 s19, s95, 0
	s_lshl_b32 s0, s10, 10
	s_ashr_i32 s1, s0, 31
	v_readlane_b32 s44, v253, 4
	s_lshl_b64 s[0:1], s[0:1], 2
	v_readlane_b32 s58, v253, 18
	v_readlane_b32 s59, v253, 19
	s_add_u32 s6, s58, s0
	v_and_b32_e32 v132, 0xfc, v133
	v_readlane_b32 s56, v253, 16
	s_addc_u32 s7, s59, s1
	v_readlane_b32 s57, v253, 17
	v_lshlrev_b32_e32 v0, 2, v132
	s_add_u32 s0, s56, s0
	s_addc_u32 s1, s57, s1
	global_load_dwordx4 v[2:5], v0, s[6:7] offset:3072
	global_load_dwordx4 v[6:9], v0, s[6:7] offset:2048
	global_load_dwordx4 v[10:13], v0, s[0:1] offset:3072
	global_load_dwordx4 v[14:17], v0, s[0:1] offset:2048
	global_load_dwordx4 v[18:21], v0, s[6:7] offset:1024
	global_load_dwordx4 v[22:25], v0, s[6:7]
	global_load_dwordx4 v[26:29], v0, s[0:1] offset:1024
	global_load_dwordx4 v[30:33], v0, s[0:1]
	s_mul_i32 s5, s10, 9
	s_add_i32 s6, s5, 9
	s_lshl_b32 s7, s34, 3
	s_add_u32 s8, s94, 0xea00000
	s_addc_u32 s9, s95, 0
	v_lshlrev_b32_e32 v0, 1, v132
	v_readlane_b32 s45, v253, 5
	v_readlane_b32 s48, v253, 8
	v_readlane_b32 s49, v253, 9
	s_cmp_eq_u32 s10, 0
	v_lshl_add_u64 v[34:35], s[94:95], 0, v[0:1]
	s_mov_b64 s[0:1], 0x4800000
	v_or_b32_e32 v136, 0x100, v132
	v_or_b32_e32 v138, 0x200, v132
	v_or_b32_e32 v140, 0x300, v132
	s_cselect_b32 s10, s49, s9
	s_cselect_b32 s11, s48, s8
	s_cselect_b32 s12, s45, s29
	s_cselect_b32 s13, s44, s28
	v_lshl_add_u64 v[142:143], v[34:35], 0, s[0:1]
	s_mov_b64 s[48:49], 0
	v_readlane_b32 s46, v253, 6
	v_readlane_b32 s47, v253, 7
	v_readlane_b32 s50, v253, 10
	v_readlane_b32 s51, v253, 11
	v_readlane_b32 s52, v253, 12
	v_readlane_b32 s53, v253, 13
	v_readlane_b32 s54, v253, 14
	v_readlane_b32 s55, v253, 15
	s_branch .LBB0_62

.Lconv_entry:
	s_and_b64 vcc, exec, s[40:41]
	v_readlane_b32 s11, v254, 54
	s_mov_b32 s10, 0x3d800000
	s_mov_b32 s13, s25
	s_mov_b32 s16, s35
	s_cbranch_vccz .LBB0_144
	s_and_b64 s[0:1], s[38:39], exec
	s_movk_i32 s0, 0x410
	s_cselect_b32 s4, s0, 0x500
	s_cmp_eq_u32 s101, 0
	s_cbranch_scc0 .Lconv_tail_mode
	s_add_i32 s100, s20, s4
	s_addk_i32 s100, 0xff00
	s_mov_b32 s101, s34
	s_branch .Lconv_chk
.Lconv_tail_mode:
	s_addk_i32 s4, 0xff00
.Lconv_chk:
	s_cmp_ge_i32 s100, s4
	s_cbranch_scc1 .LBB0_144
	v_readlane_b32 s0, v254, 55
	s_add_i32 s0, s0, 1
	s_ashr_i32 s6, s0, 1
	s_ashr_i32 s7, s6, 31
	s_ashr_i32 s1, s0, 31
	s_lshl_b64 s[8:9], s[6:7], 17
	s_lshl_b64 s[10:11], s[0:1], 22
	s_lshl_b64 s[12:13], s[6:7], 24
	s_add_u32 s0, s94, 0xf200000
	s_addc_u32 s1, s95, 0
	s_add_u32 s5, s94, 0xfa00000
	v_readlane_b32 s40, v253, 20
	s_mul_hi_i32 s14, s6, 0xc00000
	s_mul_i32 s15, s6, 0xc00000
	s_addc_u32 s6, s95, 0
	v_readlane_b32 s52, v253, 32
	v_readlane_b32 s53, v253, 33
	s_add_u32 s12, s52, s12
	s_addc_u32 s13, s53, s13
	v_readlane_b32 s41, v253, 21
	s_add_u32 s10, s40, s10
	v_readlane_b32 s44, v253, 24
	s_addc_u32 s11, s41, s11
	v_readlane_b32 s45, v253, 25
	s_add_u32 s28, s44, s8
	v_readlane_b32 s42, v253, 22
	s_addc_u32 s29, s45, s9
	v_readlane_b32 s43, v253, 23
	v_lshlrev_b32_e32 v0, 2, v133
	s_add_u32 s8, s42, s15
	s_waitcnt vmcnt(0)
	v_and_b32_e32 v2, 0xf0, v0
	v_mov_b32_e32 v3, v1
	s_addc_u32 s9, s43, s14
	v_lshl_add_u64 v[4:5], s[12:13], 0, v[2:3]
	v_lshlrev_b32_e32 v0, 3, v134
	v_lshl_add_u64 v[6:7], s[10:11], 0, v[2:3]
	v_lshl_add_u64 v[8:9], s[8:9], 0, v[2:3]
	v_ashrrev_i32_e32 v3, 3, v134
	v_add_u32_e32 v10, 0x100, v134
	s_movk_i32 s7, 0x104
	v_and_b32_e32 v0, 56, v0
	v_ashrrev_i32_e32 v35, 3, v10
	v_lshlrev_b32_e32 v10, 2, v3
	v_mad_u32_u24 v36, v0, s7, v10
	v_lshlrev_b32_e32 v10, 2, v35
	v_mad_u32_u24 v37, v0, s7, v10
	v_max_i32_e32 v10, 0x1f00, v134
	v_sub_u32_e32 v10, v10, v134
	v_add_u32_e32 v10, 0xff, v10
	v_ashrrev_i32_e32 v30, 4, v134
	v_lshrrev_b32_e32 v11, 8, v10
	v_mul_lo_u32 v31, v30, s7
	v_add_u32_e32 v11, 1, v11
	v_and_b32_e32 v12, 0x300, v10
	s_movk_i32 s7, 0x300
	v_and_b32_e32 v11, 3, v11
	v_cmp_ne_u32_e64 s[40:41], s7, v12
	s_movk_i32 s7, 0x2ff
	v_add_u32_e32 v32, 16, v30
	v_add_u32_e32 v33, 32, v30
	v_add_u32_e32 v34, 48, v30
	v_cmp_gt_i32_e64 s[38:39], s37, v134
	v_cmp_lt_u32_e64 s[42:43], s7, v10
	v_sub_u32_e32 v38, 0, v11
	v_lshlrev_b32_e32 v10, 1, v0
	s_mov_b32 s7, s100
	v_readlane_b32 s46, v253, 26
	v_readlane_b32 s47, v253, 27
	v_readlane_b32 s48, v253, 28
	v_readlane_b32 s49, v253, 29
	v_readlane_b32 s50, v253, 30
	v_readlane_b32 s51, v253, 31
	v_readlane_b32 s54, v253, 34
	v_readlane_b32 s55, v253, 35
	s_branch .LBB0_108
.LBB0_107:
	s_add_i32 s7, s7, s101
	s_cmp_ge_i32 s7, s4
	s_cbranch_scc1 .LBB0_143

.LBB0_280:
	v_readlane_b32 s76, v254, 52
	v_readlane_b32 s77, v254, 53
	v_readlane_b32 s11, v254, 54
	s_mov_b32 s10, 0x3d800000
	s_cmp_eq_u32 s74, 6
	s_cbranch_scc1 .Lconv_tail_gla
	s_cmp_eq_u32 s74, 16
	s_cbranch_scc1 .Lconv_tail_gla
	s_cmp_eq_u32 s74, 10
	s_cbranch_scc0 .LBB0_333
	s_mov_b64 s[38:39], -1
	s_mov_b64 s[26:27], 0
	s_branch .Lconv_tail_go
.Lconv_tail_gla:
	s_mov_b64 s[38:39], 0
	s_mov_b64 s[26:27], -1
.Lconv_tail_go:
	s_cmp_lt_i32 s20, 64
	s_cbranch_scc1 .LBB0_333
	s_sub_i32 s100, s20, 64
	s_cmpk_lt_i32 s20, 0x100
	s_cbranch_scc1 .Lconv_tail_idx
	s_cmpk_lt_i32 s20, 0x140
	s_cbranch_scc1 .LBB0_333
	s_sub_i32 s100, s20, 0x80
.Lconv_tail_idx:
	s_movk_i32 s101, 0x180
	s_mov_b32 s25, s13
	s_mov_b32 s35, s16
	v_lshlrev_b32_e32 v133, 2, v134
	s_mov_b64 s[40:41], -1
	s_mov_b64 s[22:23], 0
	s_branch .Lconv_entry
	s_branch .LBB0_333
